# v35 + s_setprio 1 around the scan MFMA half-step (T5 in the scan loops)
# speedup vs baseline: 1.0015x; 1.0015x over previous
.LBB0_1177:
	s_setprio 0
	s_add_i32 s29, s29, 1
	s_cmp_eq_u32 s29, 17
	s_waitcnt lgkmcnt(0)
	s_barrier
	s_cbranch_scc1 .LBB0_1189
.LBB0_1178:
	s_and_b64 s[14:15], s[4:5], exec
	s_cselect_b32 s98, 0, 1
	s_sub_u32 s98, s29, s98
	s_cmp_gt_u32 s98, 15
	s_cbranch_scc1 .LBB0_1177
	s_lshr_b32 s30, s98, 1
	s_bitcmp0_b32 s98, 0
	s_mov_b64 s[14:15], -1
	s_cbranch_scc1 .LBB0_1184
	s_setprio 1
	ds_read_b128 v[68:71], v185 offset:17152
	ds_read_b128 v[72:75], v185
	ds_read_b128 v[84:87], v185 offset:17184
	ds_read_b128 v[88:91], v185 offset:32
	s_sub_i32 s31, 7, s30
	s_and_b64 s[14:15], s[4:5], exec
	s_waitcnt lgkmcnt(2)
	v_mfma_f32_32x32x16_bf16 v[68:83], v[68:71], v[72:75], 0
	s_cselect_b32 s14, s30, s31
	s_cmp_gt_u32 s98, 7
	s_mov_b64 s[42:43], -1
	s_waitcnt lgkmcnt(0)
	v_mfma_f32_32x32x16_bf16 v[68:83], v[84:87], v[88:91], v[68:83]
	ds_read_b128 v[84:87], v185 offset:17216
	ds_read_b128 v[88:91], v185 offset:64
	ds_read_b128 v[92:95], v185 offset:17248
	ds_read_b128 v[96:99], v185 offset:96
	s_waitcnt lgkmcnt(2)
	v_mfma_f32_32x32x16_bf16 v[68:83], v[84:87], v[88:91], v[68:83]
	s_waitcnt lgkmcnt(0)
	v_mfma_f32_32x32x16_bf16 v[68:83], v[92:95], v[96:99], v[68:83]
	ds_read_b128 v[84:87], v185 offset:17280
	ds_read_b128 v[88:91], v185 offset:128
	ds_read_b128 v[92:95], v185 offset:17312
	ds_read_b128 v[96:99], v185 offset:160
	s_waitcnt lgkmcnt(2)
	v_mfma_f32_32x32x16_bf16 v[68:83], v[84:87], v[88:91], v[68:83]
	s_waitcnt lgkmcnt(0)
	v_mfma_f32_32x32x16_bf16 v[68:83], v[92:95], v[96:99], v[68:83]
	ds_read_b128 v[84:87], v185 offset:17344
	ds_read_b128 v[88:91], v185 offset:192
	ds_read_b128 v[92:95], v185 offset:17376
	ds_read_b128 v[96:99], v185 offset:224
	s_waitcnt lgkmcnt(2)
	v_mfma_f32_32x32x16_bf16 v[68:83], v[84:87], v[88:91], v[68:83]
	ds_read_b64_tr_b16 v[84:85], v186 offset:36096
	ds_read_b64_tr_b16 v[86:87], v186 offset:38656
	ds_read_b64_tr_b16 v[88:89], v186 offset:41216
	ds_read_b64_tr_b16 v[90:91], v186 offset:43776
	s_waitcnt lgkmcnt(4)
	v_mfma_f32_32x32x16_bf16 v[68:83], v[92:95], v[96:99], v[68:83]
	v_add_u32_e32 v96, 0x2000, v187
	s_nop 10
	v_cvt_pk_bf16_f32 v68, v68, v69
	v_cvt_pk_bf16_f32 v69, v70, v71
	v_cvt_pk_bf16_f32 v70, v72, v73
	v_cvt_pk_bf16_f32 v71, v74, v75
	v_and_b32_e32 v68, v149, v68
	v_and_b32_e32 v69, v151, v69
	v_and_b32_e32 v70, v153, v70
	v_and_b32_e32 v71, v155, v71
	v_cvt_pk_bf16_f32 v72, v76, v77
	v_cvt_pk_bf16_f32 v93, v78, v79
	v_cvt_pk_bf16_f32 v94, v80, v81
	v_cvt_pk_bf16_f32 v95, v82, v83
	v_and_b32_e32 v92, v157, v72
	s_waitcnt lgkmcnt(2)
	v_mfma_f32_32x32x16_bf16 v[68:83], v[68:71], v[84:87], 0
	v_and_b32_e32 v93, v159, v93
	v_and_b32_e32 v94, v161, v94
	v_and_b32_e32 v95, v163, v95
	ds_read2_b64 v[84:87], v96 offset0:64 offset1:66
	s_waitcnt lgkmcnt(1)
	v_mfma_f32_32x32x16_bf16 v[68:83], v[92:95], v[88:91], v[68:83]
	v_cvt_pk_bf16_f32 v88, v4, v5
	v_cvt_pk_bf16_f32 v89, v6, v7
	v_cvt_pk_bf16_f32 v90, v8, v9
	v_cvt_pk_bf16_f32 v91, v10, v11
	s_waitcnt lgkmcnt(0)
	s_nop 0
	v_mfma_f32_32x32x16_bf16 v[68:83], v[84:87], v[88:91], v[68:83]
	ds_read2_b64 v[84:87], v96 offset0:68 offset1:70
	v_cvt_pk_bf16_f32 v88, v12, v13
	v_cvt_pk_bf16_f32 v89, v14, v15
	v_cvt_pk_bf16_f32 v90, v16, v17
	v_cvt_pk_bf16_f32 v91, v18, v19
	s_waitcnt lgkmcnt(0)
	s_nop 0
	v_mfma_f32_32x32x16_bf16 v[68:83], v[84:87], v[88:91], v[68:83]
	ds_read2_b64 v[84:87], v96 offset0:72 offset1:74
	v_cvt_pk_bf16_f32 v88, v52, v53
	v_cvt_pk_bf16_f32 v89, v54, v55
	v_cvt_pk_bf16_f32 v90, v56, v57
	v_cvt_pk_bf16_f32 v91, v58, v59
	s_waitcnt lgkmcnt(0)
	s_nop 0
	v_mfma_f32_32x32x16_bf16 v[68:83], v[84:87], v[88:91], v[68:83]
	ds_read2_b64 v[84:87], v96 offset0:76 offset1:78
	v_cvt_pk_bf16_f32 v88, v60, v61
	v_cvt_pk_bf16_f32 v89, v62, v63
	v_cvt_pk_bf16_f32 v90, v64, v65
	v_cvt_pk_bf16_f32 v91, v66, v67
	s_waitcnt lgkmcnt(0)
	s_nop 0
	v_mfma_f32_32x32x16_bf16 v[68:83], v[84:87], v[88:91], v[68:83]
	ds_read2_b64 v[84:87], v96 offset0:80 offset1:82
	v_cvt_pk_bf16_f32 v88, v36, v37
	v_cvt_pk_bf16_f32 v89, v38, v39
	v_cvt_pk_bf16_f32 v90, v40, v41
	v_cvt_pk_bf16_f32 v91, v42, v43
	s_waitcnt lgkmcnt(0)
	s_nop 0
	v_mfma_f32_32x32x16_bf16 v[68:83], v[84:87], v[88:91], v[68:83]
	ds_read2_b64 v[84:87], v96 offset0:84 offset1:86
	v_cvt_pk_bf16_f32 v88, v44, v45
	v_cvt_pk_bf16_f32 v89, v46, v47
	v_cvt_pk_bf16_f32 v90, v48, v49
	v_cvt_pk_bf16_f32 v91, v50, v51
	s_waitcnt lgkmcnt(0)
	s_nop 0
	v_mfma_f32_32x32x16_bf16 v[68:83], v[84:87], v[88:91], v[68:83]
	ds_read2_b64 v[84:87], v96 offset0:88 offset1:90
	v_cvt_pk_bf16_f32 v88, v20, v21
	v_cvt_pk_bf16_f32 v89, v22, v23
	v_cvt_pk_bf16_f32 v90, v24, v25
	v_cvt_pk_bf16_f32 v91, v26, v27
	s_waitcnt lgkmcnt(0)
	s_nop 0
	v_mfma_f32_32x32x16_bf16 v[68:83], v[84:87], v[88:91], v[68:83]
	ds_read2_b64 v[84:87], v96 offset0:92 offset1:94
	v_cvt_pk_bf16_f32 v88, v28, v29
	v_cvt_pk_bf16_f32 v89, v30, v31
	v_cvt_pk_bf16_f32 v90, v32, v33
	v_cvt_pk_bf16_f32 v91, v34, v35
	s_waitcnt lgkmcnt(0)
	s_nop 0
	v_mfma_f32_32x32x16_bf16 v[68:83], v[84:87], v[88:91], v[68:83]
	s_cbranch_scc1 .LBB0_1181
	s_mov_b64 s[42:43], 0

.LBB0_1334:
	s_setprio 0
	s_add_i32 s19, s19, 1
	s_cmp_lg_u32 s19, 17
	s_waitcnt lgkmcnt(0)
	s_barrier
	s_cbranch_scc0 .LBB0_1331
.LBB0_1335:
	s_and_b64 s[14:15], s[4:5], exec
	s_cselect_b32 s98, 0, 1
	s_sub_u32 s98, s19, s98
	s_cmp_gt_u32 s98, 15
	s_cbranch_scc1 .LBB0_1334
	s_lshr_b32 s28, s98, 1
	s_bitcmp0_b32 s98, 0
	s_mov_b64 s[14:15], -1
	s_cbranch_scc1 .LBB0_1341
	s_setprio 1
	ds_read_b128 v[66:69], v146 offset:17152
	ds_read_b128 v[70:73], v146
	ds_read_b128 v[82:85], v146 offset:17184
	ds_read_b128 v[86:89], v146 offset:32
	s_sub_i32 s29, 7, s28
	s_and_b64 s[14:15], s[4:5], exec
	s_waitcnt lgkmcnt(2)
	v_mfma_f32_32x32x16_bf16 v[66:81], v[66:69], v[70:73], 0
	s_cselect_b32 s14, s28, s29
	s_cmp_gt_u32 s98, 7
	s_mov_b64 s[38:39], -1
	s_waitcnt lgkmcnt(0)
	v_mfma_f32_32x32x16_bf16 v[66:81], v[82:85], v[86:89], v[66:81]
	ds_read_b128 v[82:85], v146 offset:17216
	ds_read_b128 v[86:89], v146 offset:64
	ds_read_b128 v[90:93], v146 offset:17248
	ds_read_b128 v[94:97], v146 offset:96
	s_waitcnt lgkmcnt(2)
	v_mfma_f32_32x32x16_bf16 v[66:81], v[82:85], v[86:89], v[66:81]
	s_waitcnt lgkmcnt(0)
	v_mfma_f32_32x32x16_bf16 v[66:81], v[90:93], v[94:97], v[66:81]
	ds_read_b128 v[82:85], v146 offset:17280
	ds_read_b128 v[86:89], v146 offset:128
	ds_read_b128 v[90:93], v146 offset:17312
	ds_read_b128 v[94:97], v146 offset:160
	s_waitcnt lgkmcnt(2)
	v_mfma_f32_32x32x16_bf16 v[66:81], v[82:85], v[86:89], v[66:81]
	s_waitcnt lgkmcnt(0)
	v_mfma_f32_32x32x16_bf16 v[66:81], v[90:93], v[94:97], v[66:81]
	ds_read_b128 v[82:85], v146 offset:17344
	ds_read_b128 v[86:89], v146 offset:192
	ds_read_b128 v[90:93], v146 offset:17376
	ds_read_b128 v[94:97], v146 offset:224
	s_waitcnt lgkmcnt(2)
	v_mfma_f32_32x32x16_bf16 v[66:81], v[82:85], v[86:89], v[66:81]
	ds_read_b64_tr_b16 v[82:83], v202 offset:36096
	ds_read_b64_tr_b16 v[84:85], v202 offset:38656
	ds_read_b64_tr_b16 v[86:87], v202 offset:41216
	ds_read_b64_tr_b16 v[88:89], v202 offset:43776
	s_waitcnt lgkmcnt(4)
	v_mfma_f32_32x32x16_bf16 v[66:81], v[90:93], v[94:97], v[66:81]
	v_add_u32_e32 v94, 0x2000, v203
	s_nop 10
	v_cvt_pk_bf16_f32 v66, v66, v67
	v_cvt_pk_bf16_f32 v67, v68, v69
	v_cvt_pk_bf16_f32 v68, v70, v71
	v_cvt_pk_bf16_f32 v69, v72, v73
	v_and_b32_e32 v66, v178, v66
	v_and_b32_e32 v67, v179, v67
	v_and_b32_e32 v68, v180, v68
	v_and_b32_e32 v69, v181, v69
	v_cvt_pk_bf16_f32 v70, v74, v75
	v_cvt_pk_bf16_f32 v91, v76, v77
	v_cvt_pk_bf16_f32 v92, v78, v79
	v_cvt_pk_bf16_f32 v93, v80, v81
	v_and_b32_e32 v90, v182, v70
	s_waitcnt lgkmcnt(2)
	v_mfma_f32_32x32x16_bf16 v[66:81], v[66:69], v[82:85], 0
	v_and_b32_e32 v91, v191, v91
	v_and_b32_e32 v92, v194, v92
	v_and_b32_e32 v93, v195, v93
	ds_read2_b64 v[82:85], v94 offset0:64 offset1:66
	s_waitcnt lgkmcnt(1)
	v_mfma_f32_32x32x16_bf16 v[66:81], v[90:93], v[86:89], v[66:81]
	v_cvt_pk_bf16_f32 v86, v2, v3
	v_cvt_pk_bf16_f32 v87, v4, v5
	v_cvt_pk_bf16_f32 v88, v6, v7
	v_cvt_pk_bf16_f32 v89, v8, v9
	s_waitcnt lgkmcnt(0)
	s_nop 0
	v_mfma_f32_32x32x16_bf16 v[66:81], v[82:85], v[86:89], v[66:81]
	ds_read2_b64 v[82:85], v94 offset0:68 offset1:70
	v_cvt_pk_bf16_f32 v86, v10, v11
	v_cvt_pk_bf16_f32 v87, v12, v13
	v_cvt_pk_bf16_f32 v88, v14, v15
	v_cvt_pk_bf16_f32 v89, v16, v17
	s_waitcnt lgkmcnt(0)
	s_nop 0
	v_mfma_f32_32x32x16_bf16 v[66:81], v[82:85], v[86:89], v[66:81]
	ds_read2_b64 v[82:85], v94 offset0:72 offset1:74
	v_cvt_pk_bf16_f32 v86, v18, v19
	v_cvt_pk_bf16_f32 v87, v20, v21
	v_cvt_pk_bf16_f32 v88, v22, v23
	v_cvt_pk_bf16_f32 v89, v24, v25
	s_waitcnt lgkmcnt(0)
	s_nop 0
	v_mfma_f32_32x32x16_bf16 v[66:81], v[82:85], v[86:89], v[66:81]
	ds_read2_b64 v[82:85], v94 offset0:76 offset1:78
	v_cvt_pk_bf16_f32 v86, v26, v27
	v_cvt_pk_bf16_f32 v87, v28, v29
	v_cvt_pk_bf16_f32 v88, v30, v31
	v_cvt_pk_bf16_f32 v89, v32, v33
	s_waitcnt lgkmcnt(0)
	s_nop 0
	v_mfma_f32_32x32x16_bf16 v[66:81], v[82:85], v[86:89], v[66:81]
	ds_read2_b64 v[82:85], v94 offset0:80 offset1:82
	v_cvt_pk_bf16_f32 v86, v34, v35
	v_cvt_pk_bf16_f32 v87, v36, v37
	v_cvt_pk_bf16_f32 v88, v38, v39
	v_cvt_pk_bf16_f32 v89, v40, v41
	s_waitcnt lgkmcnt(0)
	s_nop 0
	v_mfma_f32_32x32x16_bf16 v[66:81], v[82:85], v[86:89], v[66:81]
	ds_read2_b64 v[82:85], v94 offset0:84 offset1:86
	v_cvt_pk_bf16_f32 v86, v42, v43
	v_cvt_pk_bf16_f32 v87, v44, v45
	v_cvt_pk_bf16_f32 v88, v46, v47
	v_cvt_pk_bf16_f32 v89, v48, v49
	s_waitcnt lgkmcnt(0)
	s_nop 0
	v_mfma_f32_32x32x16_bf16 v[66:81], v[82:85], v[86:89], v[66:81]
	ds_read2_b64 v[82:85], v94 offset0:88 offset1:90
	v_cvt_pk_bf16_f32 v86, v50, v51
	v_cvt_pk_bf16_f32 v87, v52, v53
	v_cvt_pk_bf16_f32 v88, v54, v55
	v_cvt_pk_bf16_f32 v89, v56, v57
	s_waitcnt lgkmcnt(0)
	s_nop 0
	v_mfma_f32_32x32x16_bf16 v[66:81], v[82:85], v[86:89], v[66:81]
	ds_read2_b64 v[82:85], v94 offset0:92 offset1:94
	v_cvt_pk_bf16_f32 v86, v58, v59
	v_cvt_pk_bf16_f32 v87, v60, v61
	v_cvt_pk_bf16_f32 v88, v62, v63
	v_cvt_pk_bf16_f32 v89, v64, v65
	s_waitcnt lgkmcnt(0)
	s_nop 0
	v_mfma_f32_32x32x16_bf16 v[66:81], v[82:85], v[86:89], v[66:81]
	s_cbranch_scc1 .LBB0_1338
	s_mov_b64 s[38:39], 0
